# attention queues: decode units alternate 1:1 with prompt units over the whole queue
# speedup vs baseline: 1.0026x; 1.0026x over previous
; __device__ __forceinline__ int fresh_lane() { int l; asm volatile("v_mbcnt_lo_u32_b32 %0, -1, 0\n\tv_mbcnt_hi_u32_b32 %0, -1, %0" : "=v"(l)); return l; }
; #define SEAM(k) do { if (IN(k) && IN((k) + 1)) xcd_barrier(bar, C.wave); } while (0)
; #define PH5 { phase_attention(P, C, (P.pad >> 8) & 3, P.li); }
; #define RUN(k, BODY) do { if (IN(k)) { unsigned char* ws = P.ws; LAUNDER_GPTR(ws); BODY } } while (0)
; __device__ __forceinline__ void phase_attention(const Params& P, const Ctx& C, int parts, int qset) {
;     ...
;     for (int i = 0; i < 8; ++i) { const int x = (x0 + i) & 7;
;         for (;;) {
;             __syncthreads();
;             if (C.wave == 0 && fresh_lane() == 0) *slot = __hip_atomic_fetch_add(qc + 64 * x, 1u, __ATOMIC_RELAXED, __HIP_MEMORY_SCOPE_AGENT);
;             __syncthreads();
;             const unsigned u = *slot;
;             if (u >= 128u) break;
;             const int us = __builtin_amdgcn_readfirstlane((int)u);
; __global__ void __launch_bounds__(NWAVES * 64, 2) fwd_kernel(Params P) {
;     ...
;     RUN(3, PH3); SEAM(3);
;     RUN(4, PH4);
;     RUN(5, PH5); SEAM(5);
.LBB0_1136:
	s_bitcmp1_b32 s101, 1
	s_cbranch_scc1 .Lmy_e7
	s_bitset1_b32 s101, 1
	s_cmpk_lg_i32 s68, 0x100
	s_cbranch_scc1 .Lmy_e7
	s_bitset1_b32 s101, 3
	v_readlane_b32 s99, v254, 10
	s_cmpk_lt_u32 s99, 192
	s_cbranch_scc1 .Lmy_e7
	s_and_b32 s100, s99, 31
	s_mul_i32 s100, s100, 4
	s_add_i32 s100, s100, 1
	s_bitset1_b32 s101, 0
	s_waitcnt vmcnt(0)
	s_barrier
	s_mov_b64 s[2:3], -1
	s_branch .LBB0_1192

; __device__ __forceinline__ int fresh_lane() { int l; asm volatile("v_mbcnt_lo_u32_b32 %0, -1, 0\n\tv_mbcnt_hi_u32_b32 %0, -1, %0" : "=v"(l)); return l; }
; __device__ __forceinline__ void phase_attention(const Params& P, const Ctx& C, int parts, int qset) {
;     ...
;             __syncthreads();
;             if (C.wave == 0 && fresh_lane() == 0) *slot = __hip_atomic_fetch_add(qc + 64 * x, 1u, __ATOMIC_RELAXED, __HIP_MEMORY_SCOPE_AGENT);
;             __syncthreads();
;             const unsigned u = *slot;
;             if (u >= 128u) break;
;             const int us = __builtin_amdgcn_readfirstlane((int)u);
;             int pq = -1, dq = -1;
;             if (us < 96) { const int k = us / 3, r = us - 3 * k; if (r == 0) pq = 63 - k; else dq = 2 * k + r - 1; } else pq = 127 - us;
.LBB0_1208:
	s_waitcnt lgkmcnt(0)
	s_barrier
	ds_read_b32 v0, v218
	s_movk_i32 s2, 0x7f
	s_waitcnt lgkmcnt(0)
	v_cmp_lt_u32_e32 vcc, s2, v0
	s_mov_b64 s[2:3], -1
	s_cbranch_vccnz .LBB0_1201
	v_readfirstlane_b32 s5, v0
	s_cmpk_gt_i32 s5, 0x7f
	s_cbranch_scc1 .LBB0_1213
	s_andn2_b64 vcc, exec, s[2:3]
	s_mov_b32 s4, -1
	s_cbranch_vccz .LBB0_1214

; __device__ __forceinline__ void phase_attention(const Params& P, const Ctx& C, int parts, int qset) {
;     ...
;             const int us = __builtin_amdgcn_readfirstlane((int)u);
;             int pq = -1, dq = -1;
;             if (us < 96) { const int k = us / 3, r = us - 3 * k; if (r == 0) pq = 63 - k; else dq = 2 * k + r - 1; } else pq = 127 - us;
;             if (pq >= 0) { if (parts & 1) { if (fixed_ok) attn_prompt_unit<true>(P, C, x, pq); else attn_prompt_unit<false>(P, C, x, pq); } }
.LBB0_1214:
	s_lshr_b32 s2, s5, 1
	s_and_b32 s3, s5, 1
	s_sub_i32 s4, 63, s2
	s_nop 0
	s_nop 0
	s_nop 0
	s_nop 0
	s_nop 0
	s_nop 0
	s_cmp_eq_u32 s3, 0
	s_cselect_b32 s64, s4, -1
	s_cselect_b32 s4, -1, s2
	s_cmp_lt_i32 s64, 0
	s_mov_b64 s[2:3], -1
	s_cbranch_scc0 .LBB0_1212
